# index threshold search: compare+count re-issued 4 at a time with independent carries (no nops)
# speedup vs baseline: 1.0210x; 1.0022x over previous
; __device__ __forceinline__ int half_sum_i(int v, int hf) { v = row16_sum_i(v); const int a = __builtin_amdgcn_readlane(v, 0) + __builtin_amdgcn_readlane(v, 16), b = __builtin_amdgcn_readlane(v, 32) + __builtin_amdgcn_readlane(v, 48); return hf ? b : a; }
; __device__ __forceinline__ void dsa_index_unit(const Ctx& c, int l, int b, int qb) {
;     ...
; #pragma unroll 1
;     ...
;             const unsigned cand = T | (1u << bit);
;             int cnt = 0;
; #pragma unroll
;             for (int kt = 0; kt < 64; ++kt) cnt += (key[kt] >= cand) ? 1 : 0;
;             cnt = half_sum_i(cnt, hf);
;             if (cnt >= 256) T = cand;
;         }
.LBB0_1109:
	v_lshl_or_b32 v23, 1, s0, v10
	s_add_i32 s0, s0, -1
	v_mov_b32_e32 v25, 0
	v_mov_b32_e32 v28, 0
	v_cmp_ge_u32_e64 s[56:57], v9, v23
	v_cmp_ge_u32_e64 s[58:59], v8, v23
	v_cmp_ge_u32_e64 s[60:61], v6, v23
	v_cmp_ge_u32_e32 vcc, v7, v23
	v_addc_co_u32_e64 v25, s[64:65], 0, v25, s[56:57]
	v_addc_co_u32_e64 v25, s[64:65], 0, v25, s[58:59]
	v_addc_co_u32_e64 v25, s[64:65], 0, v25, s[60:61]
	v_addc_co_u32_e32 v25, vcc, 0, v25, vcc
	v_cmp_ge_u32_e64 s[56:57], v4, v23
	v_cmp_ge_u32_e64 s[58:59], v5, v23
	v_cmp_ge_u32_e64 s[60:61], v2, v23
	v_cmp_ge_u32_e32 vcc, v3, v23
	v_addc_co_u32_e64 v28, s[64:65], 0, v28, s[56:57]
	v_addc_co_u32_e64 v28, s[64:65], 0, v28, s[58:59]
	v_addc_co_u32_e64 v28, s[64:65], 0, v28, s[60:61]
	v_addc_co_u32_e32 v28, vcc, 0, v28, vcc
	v_cmp_ge_u32_e64 s[56:57], v0, v23
	v_cmp_ge_u32_e64 s[58:59], v101, v23
	v_cmp_ge_u32_e64 s[60:61], v99, v23
	v_cmp_ge_u32_e32 vcc, v98, v23
	v_addc_co_u32_e64 v25, s[64:65], 0, v25, s[56:57]
	v_addc_co_u32_e64 v25, s[64:65], 0, v25, s[58:59]
	v_addc_co_u32_e64 v25, s[64:65], 0, v25, s[60:61]
	v_addc_co_u32_e32 v25, vcc, 0, v25, vcc
	v_cmp_ge_u32_e64 s[56:57], v96, v23
	v_cmp_ge_u32_e64 s[58:59], v95, v23
	v_cmp_ge_u32_e64 s[60:61], v93, v23
	v_cmp_ge_u32_e32 vcc, v92, v23
	v_addc_co_u32_e64 v28, s[64:65], 0, v28, s[56:57]
	v_addc_co_u32_e64 v28, s[64:65], 0, v28, s[58:59]
	v_addc_co_u32_e64 v28, s[64:65], 0, v28, s[60:61]
	v_addc_co_u32_e32 v28, vcc, 0, v28, vcc
	v_cmp_ge_u32_e64 s[56:57], v90, v23
	v_cmp_ge_u32_e64 s[58:59], v89, v23
	v_cmp_ge_u32_e64 s[60:61], v85, v23
	v_cmp_ge_u32_e32 vcc, v84, v23
	v_addc_co_u32_e64 v25, s[64:65], 0, v25, s[56:57]
	v_addc_co_u32_e64 v25, s[64:65], 0, v25, s[58:59]
	v_addc_co_u32_e64 v25, s[64:65], 0, v25, s[60:61]
	v_addc_co_u32_e32 v25, vcc, 0, v25, vcc
	v_cmp_ge_u32_e64 s[56:57], v83, v23
	v_cmp_ge_u32_e64 s[58:59], v81, v23
	v_cmp_ge_u32_e64 s[60:61], v80, v23
	v_cmp_ge_u32_e32 vcc, v78, v23
	v_addc_co_u32_e64 v28, s[64:65], 0, v28, s[56:57]
	v_addc_co_u32_e64 v28, s[64:65], 0, v28, s[58:59]
	v_addc_co_u32_e64 v28, s[64:65], 0, v28, s[60:61]
	v_addc_co_u32_e32 v28, vcc, 0, v28, vcc
	v_cmp_ge_u32_e64 s[56:57], v77, v23
	v_cmp_ge_u32_e64 s[58:59], v76, v23
	v_cmp_ge_u32_e64 s[60:61], v61, v23
	v_cmp_ge_u32_e32 vcc, v60, v23
	v_addc_co_u32_e64 v25, s[64:65], 0, v25, s[56:57]
	v_addc_co_u32_e64 v25, s[64:65], 0, v25, s[58:59]
	v_addc_co_u32_e64 v25, s[64:65], 0, v25, s[60:61]
	v_addc_co_u32_e32 v25, vcc, 0, v25, vcc
	v_cmp_ge_u32_e64 s[56:57], v58, v23
	v_cmp_ge_u32_e64 s[58:59], v57, v23
	v_cmp_ge_u32_e64 s[60:61], v55, v23
	v_cmp_ge_u32_e32 vcc, v54, v23
	v_addc_co_u32_e64 v28, s[64:65], 0, v28, s[56:57]
	v_addc_co_u32_e64 v28, s[64:65], 0, v28, s[58:59]
	v_addc_co_u32_e64 v28, s[64:65], 0, v28, s[60:61]
	v_addc_co_u32_e32 v28, vcc, 0, v28, vcc
	v_cmp_ge_u32_e64 s[56:57], v52, v23
	v_cmp_ge_u32_e64 s[58:59], v51, v23
	v_cmp_ge_u32_e64 s[60:61], v49, v23
	v_cmp_ge_u32_e32 vcc, v48, v23
	v_addc_co_u32_e64 v25, s[64:65], 0, v25, s[56:57]
	v_addc_co_u32_e64 v25, s[64:65], 0, v25, s[58:59]
	v_addc_co_u32_e64 v25, s[64:65], 0, v25, s[60:61]
	v_addc_co_u32_e32 v25, vcc, 0, v25, vcc
	v_cmp_ge_u32_e64 s[56:57], v46, v23
	v_cmp_ge_u32_e64 s[58:59], v45, v23
	v_cmp_ge_u32_e64 s[60:61], v43, v23
	v_cmp_ge_u32_e32 vcc, v42, v23
	v_addc_co_u32_e64 v28, s[64:65], 0, v28, s[56:57]
	v_addc_co_u32_e64 v28, s[64:65], 0, v28, s[58:59]
	v_addc_co_u32_e64 v28, s[64:65], 0, v28, s[60:61]
	v_addc_co_u32_e32 v28, vcc, 0, v28, vcc
	v_cmp_ge_u32_e64 s[56:57], v40, v23
	v_cmp_ge_u32_e64 s[58:59], v39, v23
	v_cmp_ge_u32_e64 s[60:61], v38, v23
	v_cmp_ge_u32_e32 vcc, v36, v23
	v_addc_co_u32_e64 v25, s[64:65], 0, v25, s[56:57]
	v_addc_co_u32_e64 v25, s[64:65], 0, v25, s[58:59]
	v_addc_co_u32_e64 v25, s[64:65], 0, v25, s[60:61]
	v_addc_co_u32_e32 v25, vcc, 0, v25, vcc
	v_cmp_ge_u32_e64 s[56:57], v35, v23
	v_cmp_ge_u32_e64 s[58:59], v33, v23
	v_cmp_ge_u32_e64 s[60:61], v32, v23
	v_cmp_ge_u32_e32 vcc, v30, v23
	v_addc_co_u32_e64 v28, s[64:65], 0, v28, s[56:57]
	v_addc_co_u32_e64 v28, s[64:65], 0, v28, s[58:59]
	v_addc_co_u32_e64 v28, s[64:65], 0, v28, s[60:61]
	v_addc_co_u32_e32 v28, vcc, 0, v28, vcc
	v_cmp_ge_u32_e64 s[56:57], v29, v23
	v_cmp_ge_u32_e64 s[58:59], v27, v23
	v_cmp_ge_u32_e64 s[60:61], v26, v23
	v_cmp_ge_u32_e32 vcc, v24, v23
	v_addc_co_u32_e64 v25, s[64:65], 0, v25, s[56:57]
	v_addc_co_u32_e64 v25, s[64:65], 0, v25, s[58:59]
	v_addc_co_u32_e64 v25, s[64:65], 0, v25, s[60:61]
	v_addc_co_u32_e32 v25, vcc, 0, v25, vcc
	v_cmp_ge_u32_e64 s[56:57], v22, v23
	v_cmp_ge_u32_e64 s[58:59], v21, v23
	v_cmp_ge_u32_e64 s[60:61], v20, v23
	v_cmp_ge_u32_e32 vcc, v19, v23
	v_addc_co_u32_e64 v28, s[64:65], 0, v28, s[56:57]
	v_addc_co_u32_e64 v28, s[64:65], 0, v28, s[58:59]
	v_addc_co_u32_e64 v28, s[64:65], 0, v28, s[60:61]
	v_addc_co_u32_e32 v28, vcc, 0, v28, vcc
	v_cmp_ge_u32_e64 s[56:57], v18, v23
	v_cmp_ge_u32_e64 s[58:59], v16, v23
	v_cmp_ge_u32_e64 s[60:61], v15, v23
	v_cmp_ge_u32_e32 vcc, v14, v23
	v_addc_co_u32_e64 v25, s[64:65], 0, v25, s[56:57]
	v_addc_co_u32_e64 v25, s[64:65], 0, v25, s[58:59]
	v_addc_co_u32_e64 v25, s[64:65], 0, v25, s[60:61]
	v_addc_co_u32_e32 v25, vcc, 0, v25, vcc
	v_cmp_ge_u32_e64 s[56:57], v13, v23
	v_cmp_ge_u32_e64 s[58:59], v12, v23
	v_cmp_ge_u32_e64 s[60:61], v11, v23
	v_cmp_ge_u32_e32 vcc, v1, v23
	v_addc_co_u32_e64 v28, s[64:65], 0, v28, s[56:57]
	v_addc_co_u32_e64 v28, s[64:65], 0, v28, s[58:59]
	v_addc_co_u32_e64 v28, s[64:65], 0, v28, s[60:61]
	v_addc_co_u32_e32 v28, vcc, 0, v28, vcc
	v_add_u32_e32 v25, v25, v28
	s_nop 1
	v_add_u32_dpp v25, v25, v25 quad_perm:[1,0,3,2] row_mask:0xf bank_mask:0xf bound_ctrl:1
	s_nop 1
	v_add_u32_dpp v25, v25, v25 quad_perm:[2,3,0,1] row_mask:0xf bank_mask:0xf bound_ctrl:1
	s_nop 1
	v_add_u32_dpp v25, v25, v25 row_half_mirror row_mask:0xf bank_mask:0xf bound_ctrl:1
	s_nop 1
	v_add_u32_dpp v25, v25, v25 row_mirror row_mask:0xf bank_mask:0xf bound_ctrl:1
	s_nop 0
	v_readlane_b32 s1, v25, 0
	v_readlane_b32 s3, v25, 16
	s_add_i32 s1, s3, s1
	v_readlane_b32 s3, v25, 32
	v_readlane_b32 s4, v25, 48
	s_add_i32 s3, s4, s3
	v_mov_b32_e32 v25, s3
	v_mov_b32_e32 v28, s1
	v_cndmask_b32_e64 v25, v25, v28, s[6:7]
	s_movk_i32 s1, 0xff
	v_cmp_lt_i32_e32 vcc, s1, v25
	s_movk_i32 s45, 0x100
	s_nop 0
	v_cndmask_b32_e32 v10, v10, v23, vcc
	v_cmp_eq_u32_e64 s[48:49], s45, v25
	s_nop 3
	s_or_b64 s[46:47], s[46:47], s[48:49]
	s_cmp_eq_u64 s[46:47], exec
	s_cbranch_scc1 .Lb0_bitdone
	s_cmp_eq_u32 s0, -1
	s_cbranch_scc0 .LBB0_1109

; __device__ __forceinline__ int half_sum_i(int v, int hf) { v = row16_sum_i(v); const int a = __builtin_amdgcn_readlane(v, 0) + __builtin_amdgcn_readlane(v, 16), b = __builtin_amdgcn_readlane(v, 32) + __builtin_amdgcn_readlane(v, 48); return hf ? b : a; }
; __device__ __forceinline__ void dsa_index_unit(const Ctx& c, int l, int b, int qb) {
;     ...
;         unsigned T = 0u;
; #pragma unroll 1
;     ...
;             const unsigned cand = T | (1u << bit);
;             int cnt = 0;
; #pragma unroll
;             for (int kt = 0; kt < 64; ++kt) cnt += (key[kt] >= cand) ? 1 : 0;
;             cnt = half_sum_i(cnt, hf);
;             if (cnt >= 256) T = cand;
;         }
.LBB0_2632:
	v_lshl_or_b32 v23, 1, s0, v10
	s_add_i32 s0, s0, -1
	v_mov_b32_e32 v25, 0
	v_mov_b32_e32 v28, 0
	v_cmp_ge_u32_e64 s[56:57], v9, v23
	v_cmp_ge_u32_e64 s[58:59], v8, v23
	v_cmp_ge_u32_e64 s[60:61], v6, v23
	v_cmp_ge_u32_e32 vcc, v7, v23
	v_addc_co_u32_e64 v25, s[64:65], 0, v25, s[56:57]
	v_addc_co_u32_e64 v25, s[64:65], 0, v25, s[58:59]
	v_addc_co_u32_e64 v25, s[64:65], 0, v25, s[60:61]
	v_addc_co_u32_e32 v25, vcc, 0, v25, vcc
	v_cmp_ge_u32_e64 s[56:57], v4, v23
	v_cmp_ge_u32_e64 s[58:59], v5, v23
	v_cmp_ge_u32_e64 s[60:61], v2, v23
	v_cmp_ge_u32_e32 vcc, v3, v23
	v_addc_co_u32_e64 v28, s[64:65], 0, v28, s[56:57]
	v_addc_co_u32_e64 v28, s[64:65], 0, v28, s[58:59]
	v_addc_co_u32_e64 v28, s[64:65], 0, v28, s[60:61]
	v_addc_co_u32_e32 v28, vcc, 0, v28, vcc
	v_cmp_ge_u32_e64 s[56:57], v0, v23
	v_cmp_ge_u32_e64 s[58:59], v101, v23
	v_cmp_ge_u32_e64 s[60:61], v99, v23
	v_cmp_ge_u32_e32 vcc, v98, v23
	v_addc_co_u32_e64 v25, s[64:65], 0, v25, s[56:57]
	v_addc_co_u32_e64 v25, s[64:65], 0, v25, s[58:59]
	v_addc_co_u32_e64 v25, s[64:65], 0, v25, s[60:61]
	v_addc_co_u32_e32 v25, vcc, 0, v25, vcc
	v_cmp_ge_u32_e64 s[56:57], v96, v23
	v_cmp_ge_u32_e64 s[58:59], v95, v23
	v_cmp_ge_u32_e64 s[60:61], v93, v23
	v_cmp_ge_u32_e32 vcc, v92, v23
	v_addc_co_u32_e64 v28, s[64:65], 0, v28, s[56:57]
	v_addc_co_u32_e64 v28, s[64:65], 0, v28, s[58:59]
	v_addc_co_u32_e64 v28, s[64:65], 0, v28, s[60:61]
	v_addc_co_u32_e32 v28, vcc, 0, v28, vcc
	v_cmp_ge_u32_e64 s[56:57], v90, v23
	v_cmp_ge_u32_e64 s[58:59], v89, v23
	v_cmp_ge_u32_e64 s[60:61], v85, v23
	v_cmp_ge_u32_e32 vcc, v84, v23
	v_addc_co_u32_e64 v25, s[64:65], 0, v25, s[56:57]
	v_addc_co_u32_e64 v25, s[64:65], 0, v25, s[58:59]
	v_addc_co_u32_e64 v25, s[64:65], 0, v25, s[60:61]
	v_addc_co_u32_e32 v25, vcc, 0, v25, vcc
	v_cmp_ge_u32_e64 s[56:57], v83, v23
	v_cmp_ge_u32_e64 s[58:59], v81, v23
	v_cmp_ge_u32_e64 s[60:61], v80, v23
	v_cmp_ge_u32_e32 vcc, v78, v23
	v_addc_co_u32_e64 v28, s[64:65], 0, v28, s[56:57]
	v_addc_co_u32_e64 v28, s[64:65], 0, v28, s[58:59]
	v_addc_co_u32_e64 v28, s[64:65], 0, v28, s[60:61]
	v_addc_co_u32_e32 v28, vcc, 0, v28, vcc
	v_cmp_ge_u32_e64 s[56:57], v77, v23
	v_cmp_ge_u32_e64 s[58:59], v76, v23
	v_cmp_ge_u32_e64 s[60:61], v61, v23
	v_cmp_ge_u32_e32 vcc, v60, v23
	v_addc_co_u32_e64 v25, s[64:65], 0, v25, s[56:57]
	v_addc_co_u32_e64 v25, s[64:65], 0, v25, s[58:59]
	v_addc_co_u32_e64 v25, s[64:65], 0, v25, s[60:61]
	v_addc_co_u32_e32 v25, vcc, 0, v25, vcc
	v_cmp_ge_u32_e64 s[56:57], v58, v23
	v_cmp_ge_u32_e64 s[58:59], v57, v23
	v_cmp_ge_u32_e64 s[60:61], v55, v23
	v_cmp_ge_u32_e32 vcc, v54, v23
	v_addc_co_u32_e64 v28, s[64:65], 0, v28, s[56:57]
	v_addc_co_u32_e64 v28, s[64:65], 0, v28, s[58:59]
	v_addc_co_u32_e64 v28, s[64:65], 0, v28, s[60:61]
	v_addc_co_u32_e32 v28, vcc, 0, v28, vcc
	v_cmp_ge_u32_e64 s[56:57], v52, v23
	v_cmp_ge_u32_e64 s[58:59], v51, v23
	v_cmp_ge_u32_e64 s[60:61], v49, v23
	v_cmp_ge_u32_e32 vcc, v48, v23
	v_addc_co_u32_e64 v25, s[64:65], 0, v25, s[56:57]
	v_addc_co_u32_e64 v25, s[64:65], 0, v25, s[58:59]
	v_addc_co_u32_e64 v25, s[64:65], 0, v25, s[60:61]
	v_addc_co_u32_e32 v25, vcc, 0, v25, vcc
	v_cmp_ge_u32_e64 s[56:57], v46, v23
	v_cmp_ge_u32_e64 s[58:59], v45, v23
	v_cmp_ge_u32_e64 s[60:61], v43, v23
	v_cmp_ge_u32_e32 vcc, v42, v23
	v_addc_co_u32_e64 v28, s[64:65], 0, v28, s[56:57]
	v_addc_co_u32_e64 v28, s[64:65], 0, v28, s[58:59]
	v_addc_co_u32_e64 v28, s[64:65], 0, v28, s[60:61]
	v_addc_co_u32_e32 v28, vcc, 0, v28, vcc
	v_cmp_ge_u32_e64 s[56:57], v40, v23
	v_cmp_ge_u32_e64 s[58:59], v39, v23
	v_cmp_ge_u32_e64 s[60:61], v38, v23
	v_cmp_ge_u32_e32 vcc, v36, v23
	v_addc_co_u32_e64 v25, s[64:65], 0, v25, s[56:57]
	v_addc_co_u32_e64 v25, s[64:65], 0, v25, s[58:59]
	v_addc_co_u32_e64 v25, s[64:65], 0, v25, s[60:61]
	v_addc_co_u32_e32 v25, vcc, 0, v25, vcc
	v_cmp_ge_u32_e64 s[56:57], v35, v23
	v_cmp_ge_u32_e64 s[58:59], v33, v23
	v_cmp_ge_u32_e64 s[60:61], v32, v23
	v_cmp_ge_u32_e32 vcc, v30, v23
	v_addc_co_u32_e64 v28, s[64:65], 0, v28, s[56:57]
	v_addc_co_u32_e64 v28, s[64:65], 0, v28, s[58:59]
	v_addc_co_u32_e64 v28, s[64:65], 0, v28, s[60:61]
	v_addc_co_u32_e32 v28, vcc, 0, v28, vcc
	v_cmp_ge_u32_e64 s[56:57], v29, v23
	v_cmp_ge_u32_e64 s[58:59], v27, v23
	v_cmp_ge_u32_e64 s[60:61], v26, v23
	v_cmp_ge_u32_e32 vcc, v24, v23
	v_addc_co_u32_e64 v25, s[64:65], 0, v25, s[56:57]
	v_addc_co_u32_e64 v25, s[64:65], 0, v25, s[58:59]
	v_addc_co_u32_e64 v25, s[64:65], 0, v25, s[60:61]
	v_addc_co_u32_e32 v25, vcc, 0, v25, vcc
	v_cmp_ge_u32_e64 s[56:57], v22, v23
	v_cmp_ge_u32_e64 s[58:59], v21, v23
	v_cmp_ge_u32_e64 s[60:61], v20, v23
	v_cmp_ge_u32_e32 vcc, v19, v23
	v_addc_co_u32_e64 v28, s[64:65], 0, v28, s[56:57]
	v_addc_co_u32_e64 v28, s[64:65], 0, v28, s[58:59]
	v_addc_co_u32_e64 v28, s[64:65], 0, v28, s[60:61]
	v_addc_co_u32_e32 v28, vcc, 0, v28, vcc
	v_cmp_ge_u32_e64 s[56:57], v18, v23
	v_cmp_ge_u32_e64 s[58:59], v16, v23
	v_cmp_ge_u32_e64 s[60:61], v15, v23
	v_cmp_ge_u32_e32 vcc, v14, v23
	v_addc_co_u32_e64 v25, s[64:65], 0, v25, s[56:57]
	v_addc_co_u32_e64 v25, s[64:65], 0, v25, s[58:59]
	v_addc_co_u32_e64 v25, s[64:65], 0, v25, s[60:61]
	v_addc_co_u32_e32 v25, vcc, 0, v25, vcc
	v_cmp_ge_u32_e64 s[56:57], v13, v23
	v_cmp_ge_u32_e64 s[58:59], v12, v23
	v_cmp_ge_u32_e64 s[60:61], v11, v23
	v_cmp_ge_u32_e32 vcc, v1, v23
	v_addc_co_u32_e64 v28, s[64:65], 0, v28, s[56:57]
	v_addc_co_u32_e64 v28, s[64:65], 0, v28, s[58:59]
	v_addc_co_u32_e64 v28, s[64:65], 0, v28, s[60:61]
	v_addc_co_u32_e32 v28, vcc, 0, v28, vcc
	v_add_u32_e32 v25, v25, v28
	s_nop 1
	v_add_u32_dpp v25, v25, v25 quad_perm:[1,0,3,2] row_mask:0xf bank_mask:0xf bound_ctrl:1
	s_nop 1
	v_add_u32_dpp v25, v25, v25 quad_perm:[2,3,0,1] row_mask:0xf bank_mask:0xf bound_ctrl:1
	s_nop 1
	v_add_u32_dpp v25, v25, v25 row_half_mirror row_mask:0xf bank_mask:0xf bound_ctrl:1
	s_nop 1
	v_add_u32_dpp v25, v25, v25 row_mirror row_mask:0xf bank_mask:0xf bound_ctrl:1
	s_nop 0
	v_readlane_b32 s1, v25, 0
	v_readlane_b32 s2, v25, 16
	s_add_i32 s1, s2, s1
	v_readlane_b32 s2, v25, 32
	v_readlane_b32 s3, v25, 48
	s_add_i32 s2, s3, s2
	v_mov_b32_e32 v25, s2
	v_mov_b32_e32 v28, s1
	v_cndmask_b32_e64 v25, v25, v28, s[6:7]
	s_movk_i32 s1, 0xff
	v_cmp_lt_i32_e32 vcc, s1, v25
	s_movk_i32 s45, 0x100
	s_nop 0
	v_cndmask_b32_e32 v10, v10, v23, vcc
	v_cmp_eq_u32_e64 s[48:49], s45, v25
	s_nop 3
	s_or_b64 s[46:47], s[46:47], s[48:49]
	s_cmp_eq_u64 s[46:47], exec
	s_cbranch_scc1 .Lb1_bitdone
	s_cmp_eq_u32 s0, -1
	s_cbranch_scc0 .LBB0_2632
